# v58 + retention output stage: the four LDS row reads issued together after the barrier with counted waits
# speedup vs baseline: 1.0035x; 1.0035x over previous
.Lret_f_end:
	s_nop 3
	v_add_u32_e32 v1, v234, v207
	v_add_u32_e32 v10, 1, v1
	v_cvt_f32_i32_e32 v14, v10
	v_mul_f32_e32 v2, v232, v14
	v_exp_f32_e32 v4, v2
	v_lshlrev_b32_e32 v2, 3, v233
	v_mul_lo_u32 v3, v1, s68
	v_add3_u32 v5, v208, v2, v3
	v_mul_f32_e32 v2, v4, v96
	v_mul_f32_e32 v3, v4, v97
	v_cvt_pk_bf16_f32 v2, v2, v3
	v_mul_f32_e32 v3, v4, v98
	v_mul_f32_e32 v6, v4, v99
	v_cvt_pk_bf16_f32 v3, v3, v6
	v_add_u32_e32 v1, 33, v1
	ds_write_b64 v5, v[2:3] offset:34816
	v_mul_f32_e32 v2, v4, v100
	v_mul_f32_e32 v3, v4, v101
	v_cvt_f32_i32_e32 v1, v1
	v_cvt_pk_bf16_f32 v2, v2, v3
	v_mul_f32_e32 v3, v4, v102
	v_mul_f32_e32 v6, v4, v103
	v_cvt_pk_bf16_f32 v3, v3, v6
	ds_write_b64 v5, v[2:3] offset:34832
	v_mul_f32_e32 v2, v4, v104
	v_mul_f32_e32 v3, v4, v105
	v_cvt_pk_bf16_f32 v2, v2, v3
	v_mul_f32_e32 v3, v4, v106
	v_mul_f32_e32 v1, v232, v1
	v_mul_f32_e32 v6, v4, v107
	v_cvt_pk_bf16_f32 v3, v3, v6
	v_exp_f32_e32 v1, v1
	ds_write_b64 v5, v[2:3] offset:34848
	v_mul_f32_e32 v2, v4, v108
	v_mul_f32_e32 v3, v4, v109
	v_cvt_pk_bf16_f32 v2, v2, v3
	v_mul_f32_e32 v3, v4, v110
	v_mul_f32_e32 v4, v4, v111
	v_cvt_pk_bf16_f32 v3, v3, v4
	ds_write_b64 v5, v[2:3] offset:34864
	v_mul_f32_e32 v2, v1, v80
	v_mul_f32_e32 v3, v1, v81
	v_cvt_pk_bf16_f32 v2, v2, v3
	v_mul_f32_e32 v3, v1, v82
	v_mul_f32_e32 v4, v1, v83
	v_cvt_pk_bf16_f32 v3, v3, v4
	ds_write_b64 v5, v[2:3] offset:43520
	v_mul_f32_e32 v2, v1, v84
	v_mul_f32_e32 v3, v1, v85
	v_cvt_pk_bf16_f32 v2, v2, v3
	v_mul_f32_e32 v3, v1, v86
	v_mul_f32_e32 v4, v1, v87
	v_cvt_pk_bf16_f32 v3, v3, v4
	ds_write_b64 v5, v[2:3] offset:43536
	v_mul_f32_e32 v2, v1, v88
	v_mul_f32_e32 v3, v1, v89
	v_cvt_pk_bf16_f32 v2, v2, v3
	v_mul_f32_e32 v3, v1, v90
	s_add_u32 s16, s40, s28
	v_mul_f32_e32 v4, v1, v91
	v_cvt_pk_bf16_f32 v3, v3, v4
	s_addc_u32 s17, s41, s34
	ds_write_b64 v5, v[2:3] offset:43552
	v_mul_f32_e32 v2, v1, v92
	v_mul_f32_e32 v3, v1, v93
	s_lshl_b64 s[18:19], s[16:17], 12
	v_cvt_pk_bf16_f32 v2, v2, v3
	v_mul_f32_e32 v3, v1, v94
	s_or_b32 s18, s18, s80
	v_mul_f32_e32 v1, v1, v95
	v_cvt_pk_bf16_f32 v3, v3, v1
	s_add_u32 s56, s26, s18
	ds_write_b64 v5, v[2:3] offset:43568
	s_waitcnt lgkmcnt(0)
	s_barrier
	s_addc_u32 s57, s27, s19
	v_sub_u32_e32 v10, 0x7f, v197
	ds_read_b128 v[2:5], v228 offset:34816
	ds_read_b128 v[236:239], v228 offset:43520
	ds_read_b128 v[240:243], v228 offset:52224
	ds_read_b128 v[244:247], v228 offset:60928
	s_add_u32 s54, s64, s18
	v_cndmask_b32_e64 v1, v10, v197, s[44:45]
	s_addc_u32 s55, s65, s19
	s_lshl_b64 s[16:17], s[16:17], 5
	v_lshl_or_b32 v8, v1, 11, v203
	s_add_u32 s18, s78, s16
	v_ashrrev_i32_e32 v9, 31, v8
	s_addc_u32 s19, s79, s17
	v_lshl_add_u64 v[6:7], v[8:9], 1, s[56:57]
	s_mov_b64 s[16:17], -1
	s_and_b64 vcc, exec, s[46:47]
	v_mbcnt_hi_u32_b32 v1, -1, v226
	s_cbranch_vccz .LBB0_982
	v_lshl_add_u64 v[8:9], v[8:9], 1, s[54:55]
	s_waitcnt lgkmcnt(3)
	v_lshlrev_b32_e32 v80, 16, v2
	v_and_b32_e32 v81, 0xffff0000, v2
	v_lshlrev_b32_e32 v82, 16, v3
	v_and_b32_e32 v83, 0xffff0000, v3
	v_lshlrev_b32_e32 v84, 16, v4
	v_and_b32_e32 v85, 0xffff0000, v4
	v_lshlrev_b32_e32 v86, 16, v5
	v_and_b32_e32 v87, 0xffff0000, v5
	s_waitcnt vmcnt(0)
	v_lshlrev_b32_e32 v88, 16, v124
	v_and_b32_e32 v89, 0xffff0000, v124
	v_lshlrev_b32_e32 v90, 16, v125
	v_and_b32_e32 v91, 0xffff0000, v125
	v_lshlrev_b32_e32 v92, 16, v126
	v_and_b32_e32 v93, 0xffff0000, v126
	v_lshlrev_b32_e32 v94, 16, v127
	v_and_b32_e32 v95, 0xffff0000, v127
	v_add_f32_e32 v80, v88, v80
	v_add_f32_e32 v81, v89, v81
	v_add_f32_e32 v82, v90, v82
	v_add_f32_e32 v83, v91, v83
	v_add_f32_e32 v84, v92, v84
	v_add_f32_e32 v85, v93, v85
	v_add_f32_e32 v86, v94, v86
	v_add_f32_e32 v87, v95, v87
	v_lshlrev_b32_e32 v94, 3, v10
	v_ashrrev_i32_e32 v95, 31, v94
	v_lshl_add_u64 v[94:95], v[94:95], 2, s[18:19]
	v_add_f32_e32 v88, v80, v81
	v_add_f32_e32 v89, v82, v83
	v_add_f32_e32 v90, v84, v85
	v_add_f32_e32 v91, v86, v87
	v_mul_f32_e32 v12, v80, v80
	v_mul_f32_e32 v13, v82, v82
	v_mul_f32_e32 v14, v84, v84
	v_mul_f32_e32 v15, v86, v86
	v_add_f32_e32 v88, v88, v89
	v_add_f32_e32 v90, v90, v91
	v_fmac_f32_e32 v12, v81, v81
	v_fmac_f32_e32 v13, v83, v83
	v_fmac_f32_e32 v14, v85, v85
	v_fmac_f32_e32 v15, v87, v87
	v_add_f32_e32 v92, v88, v90
	v_add_f32_e32 v12, v12, v13
	v_add_f32_e32 v14, v14, v15
	v_add_f32_e32 v93, v12, v14
	v_cvt_pk_bf16_f32 v80, v80, v81
	v_cvt_pk_bf16_f32 v81, v82, v83
	v_cvt_pk_bf16_f32 v82, v84, v85
	v_cvt_pk_bf16_f32 v83, v86, v87
	v_add_f32_dpp v92, v92, v92 quad_perm:[1,0,3,2] row_mask:0xf bank_mask:0xf
	v_add_f32_dpp v93, v93, v93 quad_perm:[1,0,3,2] row_mask:0xf bank_mask:0xf
	s_nop 0
	v_add_f32_dpp v92, v92, v92 quad_perm:[2,3,0,1] row_mask:0xf bank_mask:0xf
	v_add_f32_dpp v93, v93, v93 quad_perm:[2,3,0,1] row_mask:0xf bank_mask:0xf
	s_nop 0
	v_add_f32_dpp v92, v92, v92 row_ror:4 row_mask:0xf bank_mask:0xf
	v_add_f32_dpp v93, v93, v93 row_ror:4 row_mask:0xf bank_mask:0xf
	s_nop 0
	v_add_f32_dpp v92, v92, v92 row_ror:8 row_mask:0xf bank_mask:0xf
	v_add_f32_dpp v93, v93, v93 row_ror:8 row_mask:0xf bank_mask:0xf
	s_nop 0
	global_store_dwordx4 v[8:9], v[80:83], off
	s_and_saveexec_b64 s[16:17], s[8:9]
	s_cbranch_execz .LBB0_981
	global_atomic_add_f32 v[94:95], v92, off
	global_atomic_add_f32 v[94:95], v93, off offset:4

.LBB0_982:
	s_andn2_b64 vcc, exec, s[16:17]
	s_cbranch_vccnz .LBB0_984
	s_waitcnt lgkmcnt(3)
	global_store_dwordx4 v[6:7], v[2:5], off
.LBB0_984:
	v_sub_u32_e32 v10, 0x5f, v197
	s_waitcnt lgkmcnt(3)
	v_cndmask_b32_e64 v2, v10, v231, s[44:45]
	v_lshl_or_b32 v8, v2, 11, v203
	v_ashrrev_i32_e32 v9, 31, v8
	v_cndmask_b32_e64 v11, 0, 1, s[46:47]
	v_lshl_add_u64 v[6:7], v[8:9], 1, s[56:57]
	v_cmp_ne_u32_e64 s[16:17], 1, v11
	s_andn2_b64 vcc, exec, s[46:47]
	s_mov_b64 s[58:59], -1
	s_cbranch_vccnz .LBB0_988
	v_lshl_add_u64 v[8:9], v[8:9], 1, s[54:55]
	s_waitcnt lgkmcnt(2)
	v_lshlrev_b32_e32 v80, 16, v236
	v_and_b32_e32 v81, 0xffff0000, v236
	v_lshlrev_b32_e32 v82, 16, v237
	v_and_b32_e32 v83, 0xffff0000, v237
	v_lshlrev_b32_e32 v84, 16, v238
	v_and_b32_e32 v85, 0xffff0000, v238
	v_lshlrev_b32_e32 v86, 16, v239
	v_and_b32_e32 v87, 0xffff0000, v239
	v_lshlrev_b32_e32 v88, 16, v128
	v_and_b32_e32 v89, 0xffff0000, v128
	v_lshlrev_b32_e32 v90, 16, v129
	v_and_b32_e32 v91, 0xffff0000, v129
	v_lshlrev_b32_e32 v92, 16, v130
	v_and_b32_e32 v93, 0xffff0000, v130
	v_lshlrev_b32_e32 v94, 16, v131
	v_and_b32_e32 v95, 0xffff0000, v131
	v_add_f32_e32 v80, v88, v80
	v_add_f32_e32 v81, v89, v81
	v_add_f32_e32 v82, v90, v82
	v_add_f32_e32 v83, v91, v83
	v_add_f32_e32 v84, v92, v84
	v_add_f32_e32 v85, v93, v85
	v_add_f32_e32 v86, v94, v86
	v_add_f32_e32 v87, v95, v87
	v_lshlrev_b32_e32 v94, 3, v10
	v_ashrrev_i32_e32 v95, 31, v94
	v_lshl_add_u64 v[94:95], v[94:95], 2, s[18:19]
	v_add_f32_e32 v88, v80, v81
	v_add_f32_e32 v89, v82, v83
	v_add_f32_e32 v90, v84, v85
	v_add_f32_e32 v91, v86, v87
	v_mul_f32_e32 v12, v80, v80
	v_mul_f32_e32 v13, v82, v82
	v_mul_f32_e32 v14, v84, v84
	v_mul_f32_e32 v15, v86, v86
	v_add_f32_e32 v88, v88, v89
	v_add_f32_e32 v90, v90, v91
	v_fmac_f32_e32 v12, v81, v81
	v_fmac_f32_e32 v13, v83, v83
	v_fmac_f32_e32 v14, v85, v85
	v_fmac_f32_e32 v15, v87, v87
	v_add_f32_e32 v92, v88, v90
	v_add_f32_e32 v12, v12, v13
	v_add_f32_e32 v14, v14, v15
	v_add_f32_e32 v93, v12, v14
	v_cvt_pk_bf16_f32 v80, v80, v81
	v_cvt_pk_bf16_f32 v81, v82, v83
	v_cvt_pk_bf16_f32 v82, v84, v85
	v_cvt_pk_bf16_f32 v83, v86, v87
	v_add_f32_dpp v92, v92, v92 quad_perm:[1,0,3,2] row_mask:0xf bank_mask:0xf
	v_add_f32_dpp v93, v93, v93 quad_perm:[1,0,3,2] row_mask:0xf bank_mask:0xf
	s_nop 0
	v_add_f32_dpp v92, v92, v92 quad_perm:[2,3,0,1] row_mask:0xf bank_mask:0xf
	v_add_f32_dpp v93, v93, v93 quad_perm:[2,3,0,1] row_mask:0xf bank_mask:0xf
	s_nop 0
	v_add_f32_dpp v92, v92, v92 row_ror:4 row_mask:0xf bank_mask:0xf
	v_add_f32_dpp v93, v93, v93 row_ror:4 row_mask:0xf bank_mask:0xf
	s_nop 0
	v_add_f32_dpp v92, v92, v92 row_ror:8 row_mask:0xf bank_mask:0xf
	v_add_f32_dpp v93, v93, v93 row_ror:8 row_mask:0xf bank_mask:0xf
	s_nop 0
	global_store_dwordx4 v[8:9], v[80:83], off
	s_and_saveexec_b64 s[58:59], s[8:9]
	s_cbranch_execz .LBB0_987
	global_atomic_add_f32 v[94:95], v92, off
	global_atomic_add_f32 v[94:95], v93, off offset:4

.LBB0_988:
	s_andn2_b64 vcc, exec, s[58:59]
	s_cbranch_vccnz .LBB0_990
	s_waitcnt lgkmcnt(2)
	global_store_dwordx4 v[6:7], v[236:239], off
.LBB0_990:
	v_sub_u32_e32 v10, 63, v197
	s_waitcnt lgkmcnt(2)
	v_cndmask_b32_e64 v2, v10, v230, s[44:45]
	v_lshl_or_b32 v8, v2, 11, v203
	v_ashrrev_i32_e32 v9, 31, v8
	v_lshl_add_u64 v[6:7], v[8:9], 1, s[56:57]
	s_and_b64 vcc, exec, s[16:17]
	s_mov_b64 s[58:59], -1
	s_cbranch_vccnz .LBB0_994
	v_lshl_add_u64 v[8:9], v[8:9], 1, s[54:55]
	s_waitcnt lgkmcnt(1)
	v_lshlrev_b32_e32 v80, 16, v240
	v_and_b32_e32 v81, 0xffff0000, v240
	v_lshlrev_b32_e32 v82, 16, v241
	v_and_b32_e32 v83, 0xffff0000, v241
	v_lshlrev_b32_e32 v84, 16, v242
	v_and_b32_e32 v85, 0xffff0000, v242
	v_lshlrev_b32_e32 v86, 16, v243
	v_and_b32_e32 v87, 0xffff0000, v243
	v_lshlrev_b32_e32 v88, 16, v132
	v_and_b32_e32 v89, 0xffff0000, v132
	v_lshlrev_b32_e32 v90, 16, v133
	v_and_b32_e32 v91, 0xffff0000, v133
	v_lshlrev_b32_e32 v92, 16, v134
	v_and_b32_e32 v93, 0xffff0000, v134
	v_lshlrev_b32_e32 v94, 16, v135
	v_and_b32_e32 v95, 0xffff0000, v135
	v_add_f32_e32 v80, v88, v80
	v_add_f32_e32 v81, v89, v81
	v_add_f32_e32 v82, v90, v82
	v_add_f32_e32 v83, v91, v83
	v_add_f32_e32 v84, v92, v84
	v_add_f32_e32 v85, v93, v85
	v_add_f32_e32 v86, v94, v86
	v_add_f32_e32 v87, v95, v87
	v_lshlrev_b32_e32 v94, 3, v10
	v_ashrrev_i32_e32 v95, 31, v94
	v_lshl_add_u64 v[94:95], v[94:95], 2, s[18:19]
	v_add_f32_e32 v88, v80, v81
	v_add_f32_e32 v89, v82, v83
	v_add_f32_e32 v90, v84, v85
	v_add_f32_e32 v91, v86, v87
	v_mul_f32_e32 v12, v80, v80
	v_mul_f32_e32 v13, v82, v82
	v_mul_f32_e32 v14, v84, v84
	v_mul_f32_e32 v15, v86, v86
	v_add_f32_e32 v88, v88, v89
	v_add_f32_e32 v90, v90, v91
	v_fmac_f32_e32 v12, v81, v81
	v_fmac_f32_e32 v13, v83, v83
	v_fmac_f32_e32 v14, v85, v85
	v_fmac_f32_e32 v15, v87, v87
	v_add_f32_e32 v92, v88, v90
	v_add_f32_e32 v12, v12, v13
	v_add_f32_e32 v14, v14, v15
	v_add_f32_e32 v93, v12, v14
	v_cvt_pk_bf16_f32 v80, v80, v81
	v_cvt_pk_bf16_f32 v81, v82, v83
	v_cvt_pk_bf16_f32 v82, v84, v85
	v_cvt_pk_bf16_f32 v83, v86, v87
	v_add_f32_dpp v92, v92, v92 quad_perm:[1,0,3,2] row_mask:0xf bank_mask:0xf
	v_add_f32_dpp v93, v93, v93 quad_perm:[1,0,3,2] row_mask:0xf bank_mask:0xf
	s_nop 0
	v_add_f32_dpp v92, v92, v92 quad_perm:[2,3,0,1] row_mask:0xf bank_mask:0xf
	v_add_f32_dpp v93, v93, v93 quad_perm:[2,3,0,1] row_mask:0xf bank_mask:0xf
	s_nop 0
	v_add_f32_dpp v92, v92, v92 row_ror:4 row_mask:0xf bank_mask:0xf
	v_add_f32_dpp v93, v93, v93 row_ror:4 row_mask:0xf bank_mask:0xf
	s_nop 0
	v_add_f32_dpp v92, v92, v92 row_ror:8 row_mask:0xf bank_mask:0xf
	v_add_f32_dpp v93, v93, v93 row_ror:8 row_mask:0xf bank_mask:0xf
	s_nop 0
	global_store_dwordx4 v[8:9], v[80:83], off
	s_and_saveexec_b64 s[58:59], s[8:9]
	s_cbranch_execz .LBB0_993
	global_atomic_add_f32 v[94:95], v92, off
	global_atomic_add_f32 v[94:95], v93, off offset:4

.LBB0_994:
	s_andn2_b64 vcc, exec, s[58:59]
	s_cbranch_vccnz .LBB0_996
	s_waitcnt lgkmcnt(1)
	global_store_dwordx4 v[6:7], v[240:243], off
.LBB0_996:
	v_sub_u32_e32 v10, 31, v197
	s_waitcnt lgkmcnt(1)
	v_cndmask_b32_e64 v2, v10, v229, s[44:45]
	v_lshl_or_b32 v8, v2, 11, v203
	v_ashrrev_i32_e32 v9, 31, v8
	v_lshl_add_u64 v[6:7], v[8:9], 1, s[56:57]
	s_and_b64 vcc, exec, s[16:17]
	s_mov_b64 s[16:17], -1
	s_cbranch_vccnz .LBB0_1000
	v_lshl_add_u64 v[8:9], v[8:9], 1, s[54:55]
	s_waitcnt lgkmcnt(0)
	v_lshlrev_b32_e32 v80, 16, v244
	v_and_b32_e32 v81, 0xffff0000, v244
	v_lshlrev_b32_e32 v82, 16, v245
	v_and_b32_e32 v83, 0xffff0000, v245
	v_lshlrev_b32_e32 v84, 16, v246
	v_and_b32_e32 v85, 0xffff0000, v246
	v_lshlrev_b32_e32 v86, 16, v247
	v_and_b32_e32 v87, 0xffff0000, v247
	v_lshlrev_b32_e32 v88, 16, v136
	v_and_b32_e32 v89, 0xffff0000, v136
	v_lshlrev_b32_e32 v90, 16, v137
	v_and_b32_e32 v91, 0xffff0000, v137
	v_lshlrev_b32_e32 v92, 16, v138
	v_and_b32_e32 v93, 0xffff0000, v138
	v_lshlrev_b32_e32 v94, 16, v139
	v_and_b32_e32 v95, 0xffff0000, v139
	v_add_f32_e32 v80, v88, v80
	v_add_f32_e32 v81, v89, v81
	v_add_f32_e32 v82, v90, v82
	v_add_f32_e32 v83, v91, v83
	v_add_f32_e32 v84, v92, v84
	v_add_f32_e32 v85, v93, v85
	v_add_f32_e32 v86, v94, v86
	v_add_f32_e32 v87, v95, v87
	v_lshlrev_b32_e32 v94, 3, v10
	v_ashrrev_i32_e32 v95, 31, v94
	v_lshl_add_u64 v[94:95], v[94:95], 2, s[18:19]
	v_add_f32_e32 v88, v80, v81
	v_add_f32_e32 v89, v82, v83
	v_add_f32_e32 v90, v84, v85
	v_add_f32_e32 v91, v86, v87
	v_mul_f32_e32 v12, v80, v80
	v_mul_f32_e32 v13, v82, v82
	v_mul_f32_e32 v14, v84, v84
	v_mul_f32_e32 v15, v86, v86
	v_add_f32_e32 v88, v88, v89
	v_add_f32_e32 v90, v90, v91
	v_fmac_f32_e32 v12, v81, v81
	v_fmac_f32_e32 v13, v83, v83
	v_fmac_f32_e32 v14, v85, v85
	v_fmac_f32_e32 v15, v87, v87
	v_add_f32_e32 v92, v88, v90
	v_add_f32_e32 v12, v12, v13
	v_add_f32_e32 v14, v14, v15
	v_add_f32_e32 v93, v12, v14
	v_cvt_pk_bf16_f32 v80, v80, v81
	v_cvt_pk_bf16_f32 v81, v82, v83
	v_cvt_pk_bf16_f32 v82, v84, v85
	v_cvt_pk_bf16_f32 v83, v86, v87
	v_add_f32_dpp v92, v92, v92 quad_perm:[1,0,3,2] row_mask:0xf bank_mask:0xf
	v_add_f32_dpp v93, v93, v93 quad_perm:[1,0,3,2] row_mask:0xf bank_mask:0xf
	s_nop 0
	v_add_f32_dpp v92, v92, v92 quad_perm:[2,3,0,1] row_mask:0xf bank_mask:0xf
	v_add_f32_dpp v93, v93, v93 quad_perm:[2,3,0,1] row_mask:0xf bank_mask:0xf
	s_nop 0
	v_add_f32_dpp v92, v92, v92 row_ror:4 row_mask:0xf bank_mask:0xf
	v_add_f32_dpp v93, v93, v93 row_ror:4 row_mask:0xf bank_mask:0xf
	s_nop 0
	v_add_f32_dpp v92, v92, v92 row_ror:8 row_mask:0xf bank_mask:0xf
	v_add_f32_dpp v93, v93, v93 row_ror:8 row_mask:0xf bank_mask:0xf
	s_nop 0
	global_store_dwordx4 v[8:9], v[80:83], off
	s_and_saveexec_b64 s[16:17], s[8:9]
	s_cbranch_execz .LBB0_999
	global_atomic_add_f32 v[94:95], v92, off
	global_atomic_add_f32 v[94:95], v93, off offset:4

.LBB0_1000:
	s_andn2_b64 vcc, exec, s[16:17]
	s_cbranch_vccnz .LBB0_1002
	s_waitcnt lgkmcnt(0)
	global_store_dwordx4 v[6:7], v[244:247], off
